# attention loop: address constants folded into running bases; staging writes, next-tile loads and row-sum interleaved into the PV MFMA gaps
# speedup vs baseline: 1.1416x; 1.0142x over previous
.LBB0_265:
	v_lshlrev_b32_e32 v150, 3, v34
	v_exp_f32_e32 v34, v2
	v_exp_f32_e32 v35, v18
	v_exp_f32_e32 v18, v3
	v_exp_f32_e32 v19, v19
	s_waitcnt lgkmcnt(0)
	v_exp_f32_e32 v36, v4
	v_exp_f32_e32 v37, v20
	v_exp_f32_e32 v20, v5
	v_exp_f32_e32 v21, v21
	v_pk_add_f32 v[2:3], v[34:35], 0 op_sel_hi:[1,0]
	v_exp_f32_e32 v38, v6
	v_exp_f32_e32 v39, v22
	v_pk_add_f32 v[2:3], v[2:3], v[18:19]
	v_exp_f32_e32 v6, v7
	v_exp_f32_e32 v7, v23
	v_pk_add_f32 v[2:3], v[36:37], v[2:3]
	v_exp_f32_e32 v22, v8
	v_exp_f32_e32 v23, v24
	v_pk_add_f32 v[2:3], v[20:21], v[2:3]
	v_exp_f32_e32 v8, v9
	v_exp_f32_e32 v9, v25
	v_pk_add_f32 v[2:3], v[38:39], v[2:3]
	v_exp_f32_e32 v24, v10
	v_exp_f32_e32 v25, v26
	v_pk_add_f32 v[2:3], v[6:7], v[2:3]
	v_exp_f32_e32 v10, v11
	v_exp_f32_e32 v11, v27
	v_pk_add_f32 v[2:3], v[22:23], v[2:3]
	v_exp_f32_e32 v26, v12
	v_exp_f32_e32 v27, v28
	v_pk_add_f32 v[2:3], v[8:9], v[2:3]
	v_exp_f32_e32 v12, v13
	v_exp_f32_e32 v13, v29
	v_pk_add_f32 v[2:3], v[24:25], v[2:3]
	v_exp_f32_e32 v28, v14
	v_exp_f32_e32 v29, v30
	v_pk_add_f32 v[2:3], v[10:11], v[2:3]
	v_exp_f32_e32 v14, v15
	v_exp_f32_e32 v15, v31
	v_pk_add_f32 v[2:3], v[26:27], v[2:3]
	v_exp_f32_e32 v30, v16
	v_exp_f32_e32 v31, v32
	v_pk_add_f32 v[2:3], v[12:13], v[2:3]
	v_exp_f32_e32 v16, v17
	v_exp_f32_e32 v17, v33
	v_pk_add_f32 v[2:3], v[28:29], v[2:3]
	v_and_b32_e32 v184, 63, v236
	v_pk_add_f32 v[2:3], v[14:15], v[2:3]
	v_ashrrev_i32_e32 v161, 31, v160
	v_pk_add_f32 v[2:3], v[30:31], v[2:3]
	v_cvt_pk_bf16_f32 v4, v38, v6
	v_pk_add_f32 v[128:129], v[16:17], v[2:3]
	v_cvt_pk_bf16_f32 v2, v34, v18
	v_cvt_pk_bf16_f32 v3, v36, v20
	v_cvt_pk_bf16_f32 v5, v22, v8
	v_cvt_pk_bf16_f32 v118, v24, v10
	v_cvt_pk_bf16_f32 v119, v26, v12
	v_cvt_pk_bf16_f32 v120, v28, v14
	v_cvt_pk_bf16_f32 v121, v30, v16
	v_cvt_pk_bf16_f32 v124, v35, v19
	v_cvt_pk_bf16_f32 v125, v37, v21
	v_cvt_pk_bf16_f32 v126, v39, v7
	v_cvt_pk_bf16_f32 v127, v23, v9
	v_cvt_pk_bf16_f32 v156, v25, v11
	v_cvt_pk_bf16_f32 v157, v27, v13
	v_cvt_pk_bf16_f32 v158, v29, v15
	v_cvt_pk_bf16_f32 v159, v31, v17
	s_ashr_i32 s5, s4, 31
	s_setprio 1
	v_sub_u32_e32 v6, v146, v150
	v_mad_u32_u24 v10, v116, s70, v6
	v_add_u32_e32 v11, 0x4800, v10
	ds_read2_b64 v[6:9], v11 offset1:2
	v_add_u32_e32 v132, 0x7800, v10
	ds_read2_b64 v[162:165], v132 offset0:100 offset1:102
	v_mul_u32_u24_e32 v186, 0x88, v116
	v_add_f32_e32 v116, v128, v129
	v_add_f32_e32 v185, 0, v116
	s_waitcnt lgkmcnt(1)
	v_mfma_f32_32x32x16_bf16 v[50:65], v[6:9], v[2:5], 0
	ds_read2_b64 v[6:9], v11 offset0:4 offset1:6
	s_waitcnt lgkmcnt(0)
	v_mfma_f32_32x32x16_bf16 v[50:65], v[6:9], v[118:121], v[50:65]
	ds_read2_b64 v[6:9], v11 offset0:8 offset1:10
	s_waitcnt lgkmcnt(0)
	v_mfma_f32_32x32x16_bf16 v[50:65], v[6:9], v[124:127], v[50:65]
	ds_read2_b64 v[6:9], v11 offset0:12 offset1:14
	v_add_u32_e32 v11, 0x5800, v10
	s_waitcnt lgkmcnt(0)
	v_mfma_f32_32x32x16_bf16 v[50:65], v[6:9], v[156:159], v[50:65]
	ds_read2_b64 v[6:9], v11 offset0:32 offset1:34
	s_waitcnt lgkmcnt(0)
	v_mfma_f32_32x32x16_bf16 v[34:49], v[6:9], v[2:5], 0
	ds_read2_b64 v[6:9], v11 offset0:36 offset1:38
	s_waitcnt lgkmcnt(0)
	v_mfma_f32_32x32x16_bf16 v[34:49], v[6:9], v[118:121], v[34:49]
	ds_read2_b64 v[6:9], v11 offset0:40 offset1:42
	s_waitcnt lgkmcnt(0)
	v_mfma_f32_32x32x16_bf16 v[34:49], v[6:9], v[124:127], v[34:49]
	ds_read2_b64 v[6:9], v11 offset0:44 offset1:46
	v_add_u32_e32 v11, 0x6800, v10
	s_waitcnt lgkmcnt(0)
	v_mfma_f32_32x32x16_bf16 v[34:49], v[6:9], v[156:159], v[34:49]
	ds_read2_b64 v[6:9], v11 offset0:64 offset1:66
	s_waitcnt lgkmcnt(0)
	v_mfma_f32_32x32x16_bf16 v[18:33], v[6:9], v[2:5], 0
	ds_read2_b64 v[6:9], v11 offset0:68 offset1:70
	s_waitcnt lgkmcnt(0)
	v_mfma_f32_32x32x16_bf16 v[18:33], v[6:9], v[118:121], v[18:33]
	ds_read2_b64 v[6:9], v11 offset0:72 offset1:74
	s_waitcnt lgkmcnt(0)
	v_mfma_f32_32x32x16_bf16 v[18:33], v[6:9], v[124:127], v[18:33]
	ds_read2_b64 v[6:9], v11 offset0:76 offset1:78
	s_waitcnt lgkmcnt(0)
	v_mfma_f32_32x32x16_bf16 v[18:33], v[6:9], v[156:159], v[18:33]
	ds_read2_b64 v[6:9], v132 offset0:96 offset1:98
	s_waitcnt lgkmcnt(0)
	v_mfma_f32_32x32x16_bf16 v[2:17], v[6:9], v[2:5], 0
	v_mfma_f32_32x32x16_bf16 v[2:17], v[162:165], v[118:121], v[2:17]
	ds_read2_b64 v[118:121], v132 offset0:104 offset1:106
	s_waitcnt lgkmcnt(0)
	v_mfma_f32_32x32x16_bf16 v[2:17], v[118:121], v[124:127], v[2:17]
	ds_read2_b64 v[118:121], v132 offset0:108 offset1:110
	s_waitcnt lgkmcnt(0)
	v_mfma_f32_32x32x16_bf16 v[2:17], v[118:121], v[156:159], v[2:17]
	s_setprio 0
	s_waitcnt vmcnt(0)
	ds_write_b128 v117, v[94:97] offset:35840
	ds_write_b128 v117, v[90:93] offset:40448
	ds_write_b128 v117, v[86:89] offset:45056
	ds_write_b128 v117, v[82:85] offset:49664
	v_add_u32_e32 v82, 0xd400, v0
	ds_write2_b64 v82, v[78:79], v[80:81] offset1:1
	v_add_u32_e32 v78, 0xe500, v0
	v_add_u32_e32 v0, 0xf600, v0
	ds_write2_b64 v0, v[70:71], v[72:73] offset1:1
	v_add_u32_e32 v0, 0x3300, v82
	s_movk_i32 s1, 0x5000
	ds_write2_b64 v0, v[66:67], v[68:69] offset1:1
	v_add_co_u32_e32 v66, vcc, s1, v114
	ds_write2_b64 v78, v[74:75], v[76:77] offset1:1
	s_nop 0
	v_addc_co_u32_e32 v67, vcc, 0, v115, vcc
	global_load_dwordx4 v[114:117], v[66:67], off offset:-4096
	global_load_dwordx4 v[118:121], v[66:67], off
	v_add_co_u32_e32 v66, vcc, s1, v122
	v_readlane_b32 s36, v252, 4
	s_nop 0
	v_addc_co_u32_e32 v67, vcc, 0, v123, vcc
	global_load_dwordx4 v[122:125], v[66:67], off offset:-4096
	global_load_dwordx4 v[126:129], v[66:67], off
	s_nop 0
	global_load_dwordx4 v[130:133], v[130:131], off offset:256
	s_nop 0
	global_load_dwordx4 v[134:137], v[134:135], off offset:256
	s_nop 0
	global_load_dwordx4 v[138:141], v[138:139], off offset:256
	s_nop 0
	global_load_dwordx4 v[142:145], v[142:143], off offset:256
	v_readlane_b32 s50, v252, 18
	v_readlane_b32 s51, v252, 19
	s_add_u32 s26, s50, s21
	v_lshlrev_b32_e32 v66, 4, v236
	s_addc_u32 s27, s51, s20
	s_lshl_b64 s[4:5], s[4:5], 8
	v_and_b32_e32 v66, 0x1f80, v66
	v_mov_b32_e32 v67, v1
	s_or_b32 s20, s4, 0x80
	v_lshl_add_u64 v[156:157], s[26:27], 0, v[66:67]
	s_mul_i32 s24, s13, s5
	s_mul_hi_u32 s26, s13, s20
	s_add_i32 s24, s26, s24
	s_mul_i32 s26, s13, s20
	s_add_u32 s26, s50, s26
	s_addc_u32 s27, s51, s24
	v_lshl_add_u64 v[158:159], s[26:27], 0, v[66:67]
	v_lshlrev_b64 v[66:67], 1, v[160:161]
	s_mov_b32 s21, s5
	v_lshl_add_u64 v[68:69], s[4:5], 0, v[66:67]
	v_mov_b64_e32 v[70:71], s[50:51]
	v_lshl_add_u64 v[72:73], v[68:69], 0, 64
	v_lshl_add_u64 v[66:67], s[20:21], 0, v[66:67]
	v_mad_u64_u32 v[160:161], s[4:5], s13, v68, v[70:71]
	v_mad_u64_u32 v[162:163], s[4:5], s13, v72, v[70:71]
	v_mad_u64_u32 v[164:165], s[4:5], s13, v66, v[70:71]
	s_mov_b64 s[4:5], 0xc0
	v_mad_i32_i24 v165, s13, v67, v165
	v_lshl_add_u64 v[66:67], v[68:69], 0, s[4:5]
	v_and_b32_e32 v0, 7, v236
	v_mad_u64_u32 v[166:167], s[4:5], s13, v66, v[70:71]
	v_lshlrev_b32_e32 v0, 4, v0
	v_mad_i32_i24 v161, s13, v69, v161
	v_mad_i32_i24 v163, s13, v73, v163
	v_mad_i32_i24 v167, s13, v67, v167
	v_mov_b32_e32 v250, 0xe42b800
	v_mov_b32_e32 v251, 0
	v_lshl_add_u64 v[156:157], v[156:157], 0, v[0:1]
	v_lshl_add_u64 v[156:157], v[156:157], 0, v[250:251]
	v_lshl_add_u64 v[158:159], v[158:159], 0, v[0:1]
	v_lshl_add_u64 v[158:159], v[158:159], 0, v[250:251]
	v_mov_b32_e32 v250, 0xeca5000
	v_lshl_add_u64 v[160:161], v[160:161], 0, v[0:1]
	v_lshl_add_u64 v[160:161], v[160:161], 0, v[250:251]
	v_lshl_add_u64 v[162:163], v[162:163], 0, v[0:1]
	v_lshl_add_u64 v[162:163], v[162:163], 0, v[250:251]
	v_lshl_add_u64 v[164:165], v[164:165], 0, v[0:1]
	v_lshl_add_u64 v[164:165], v[164:165], 0, v[250:251]
	v_lshl_add_u64 v[166:167], v[166:167], 0, v[0:1]
	v_lshl_add_u64 v[166:167], v[166:167], 0, v[250:251]
	s_mov_b32 s4, 3
	s_waitcnt lgkmcnt(0)
	s_barrier
	v_readlane_b32 s37, v252, 5
	v_readlane_b32 s38, v252, 6
	v_readlane_b32 s39, v252, 7
	v_readlane_b32 s40, v252, 8
	v_readlane_b32 s41, v252, 9
	v_readlane_b32 s42, v252, 10
	v_readlane_b32 s43, v252, 11
	v_readlane_b32 s44, v252, 12
	v_readlane_b32 s45, v252, 13
	v_readlane_b32 s46, v252, 14
	v_readlane_b32 s47, v252, 15
	v_readlane_b32 s48, v252, 16
	v_readlane_b32 s49, v252, 17
	s_branch .LBB0_267
.LBB0_266:
	s_mov_b64 s[20:21], 0x2000
	s_add_i32 s4, s4, 1
	v_lshl_add_u64 v[156:157], v[156:157], 0, s[20:21]
	v_lshl_add_u64 v[158:159], v[158:159], 0, s[20:21]
	s_mov_b64 s[20:21], 0x80
	s_add_i32 s5, s12, s4
	v_lshl_add_u64 v[160:161], v[160:161], 0, s[20:21]
	v_lshl_add_u64 v[162:163], v[162:163], 0, s[20:21]
	v_lshl_add_u64 v[164:165], v[164:165], 0, s[20:21]
	v_lshl_add_u64 v[166:167], v[166:167], 0, s[20:21]
	s_cmp_eq_u32 s5, 2
	v_add_f32_e32 v185, v185, v238
	s_waitcnt lgkmcnt(0)
	s_barrier
	s_cbranch_scc1 .LBB0_272

.LBB0_269:
	v_exp_f32_e32 v180, v82
	v_exp_f32_e32 v181, v66
	v_exp_f32_e32 v178, v83
	v_exp_f32_e32 v179, v67
	v_exp_f32_e32 v176, v84
	v_exp_f32_e32 v177, v68
	v_exp_f32_e32 v174, v85
	v_exp_f32_e32 v175, v69
	v_exp_f32_e32 v172, v86
	v_exp_f32_e32 v173, v70
	v_exp_f32_e32 v170, v87
	v_exp_f32_e32 v171, v71
	v_exp_f32_e32 v168, v88
	v_exp_f32_e32 v169, v72
	v_exp_f32_e32 v88, v89
	v_exp_f32_e32 v89, v73
	v_exp_f32_e32 v86, v90
	v_exp_f32_e32 v87, v74
	v_exp_f32_e32 v84, v91
	v_exp_f32_e32 v85, v75
	v_exp_f32_e32 v82, v92
	v_exp_f32_e32 v83, v76
	v_exp_f32_e32 v74, v93
	v_exp_f32_e32 v75, v77
	v_exp_f32_e32 v72, v94
	v_exp_f32_e32 v73, v78
	v_exp_f32_e32 v70, v95
	v_exp_f32_e32 v71, v79
	v_exp_f32_e32 v68, v96
	v_exp_f32_e32 v69, v80
	v_exp_f32_e32 v66, v97
	v_exp_f32_e32 v67, v81
	v_cvt_pk_bf16_f32 v76, v180, v178
	v_cvt_pk_bf16_f32 v77, v176, v174
	v_cvt_pk_bf16_f32 v78, v172, v170
	v_cvt_pk_bf16_f32 v79, v168, v88
	v_cvt_pk_bf16_f32 v90, v86, v84
	v_cvt_pk_bf16_f32 v91, v82, v74
	v_cvt_pk_bf16_f32 v92, v72, v70
	v_cvt_pk_bf16_f32 v93, v68, v66
	v_cvt_pk_bf16_f32 v94, v181, v179
	v_cvt_pk_bf16_f32 v95, v177, v175
	v_cvt_pk_bf16_f32 v96, v173, v171
	v_cvt_pk_bf16_f32 v97, v169, v89
	v_cvt_pk_bf16_f32 v188, v87, v85
	v_cvt_pk_bf16_f32 v189, v83, v75
	v_cvt_pk_bf16_f32 v190, v73, v71
	v_cvt_pk_bf16_f32 v191, v69, v67
	s_setprio 1
	v_add3_u32 v80, s5, v150, v186
	v_add_u32_e32 v246, 0x4800, v80
	v_add_u32_e32 v247, 0x5800, v80
	v_add_u32_e32 v248, 0x6800, v80
	v_add_u32_e32 v249, 0x7800, v80
	ds_read2_b64 v[192:195], v246 offset0:0 offset1:2
	ds_read2_b64 v[206:209], v247 offset0:32 offset1:34
	ds_read2_b64 v[210:213], v248 offset0:64 offset1:66
	ds_read2_b64 v[222:225], v249 offset0:96 offset1:98
	s_waitcnt lgkmcnt(3)
	v_mfma_f32_32x32x16_bf16 v[50:65], v[192:195], v[76:79], v[50:65]
	ds_read2_b64 v[192:195], v246 offset0:4 offset1:6
	s_add_i32 s5, s4, -1
	s_bitcmp1_b32 s5, 0
	s_cselect_b32 s5, 0x8c00, 0
	v_add_f32_e32 v238, v180, v181
	v_add_f32_e32 v239, v172, v173
	s_waitcnt lgkmcnt(3)
	v_mfma_f32_32x32x16_bf16 v[34:49], v[206:209], v[76:79], v[34:49]
	ds_read2_b64 v[206:209], v247 offset0:36 offset1:38
	v_lshlrev_b32_e32 v250, 1, v153
	v_add3_u32 v250, s5, v250, v152
	v_add_f32_e32 v240, v86, v87
	v_add_f32_e32 v241, v72, v73
	s_waitcnt lgkmcnt(3)
	v_mfma_f32_32x32x16_bf16 v[18:33], v[210:213], v[76:79], v[18:33]
	ds_read2_b64 v[210:213], v248 offset0:68 offset1:70
	s_waitcnt vmcnt(0)
	ds_write_b128 v250, v[114:117]
	v_add_f32_e32 v238, v238, v178
	v_add_f32_e32 v239, v239, v170
	s_waitcnt lgkmcnt(4)
	v_mfma_f32_32x32x16_bf16 v[2:17], v[222:225], v[76:79], v[2:17]
	ds_read2_b64 v[222:225], v249 offset0:100 offset1:102
	ds_write_b128 v250, v[118:121] offset:4608
	v_add_f32_e32 v240, v240, v84
	v_add_f32_e32 v241, v241, v70
	s_waitcnt lgkmcnt(5)
	v_mfma_f32_32x32x16_bf16 v[50:65], v[192:195], v[90:93], v[50:65]
	ds_read2_b64 v[192:195], v246 offset0:8 offset1:10
	ds_write_b128 v250, v[122:125] offset:9216
	v_add_f32_e32 v238, v238, v179
	v_add_f32_e32 v239, v239, v171
	s_waitcnt lgkmcnt(6)
	v_mfma_f32_32x32x16_bf16 v[34:49], v[206:209], v[90:93], v[34:49]
	ds_read2_b64 v[206:209], v247 offset0:40 offset1:42
	ds_write_b128 v250, v[126:129] offset:13824
	v_add_f32_e32 v240, v240, v85
	v_add_f32_e32 v241, v241, v71
	s_waitcnt lgkmcnt(7)
	v_mfma_f32_32x32x16_bf16 v[18:33], v[210:213], v[90:93], v[18:33]
	ds_read2_b64 v[210:213], v248 offset0:72 offset1:74
	v_lshlrev_b32_e32 v251, 1, v182
	v_add3_u32 v251, s5, v251, v152
	v_add_f32_e32 v238, v238, v176
	v_add_f32_e32 v239, v239, v168
	s_waitcnt lgkmcnt(6)
	v_mfma_f32_32x32x16_bf16 v[2:17], v[222:225], v[90:93], v[2:17]
	ds_read2_b64 v[222:225], v249 offset0:104 offset1:106
	v_add_u32_e32 v214, 0x4800, v251
	ds_write2_b64 v214, v[130:131], v[132:133] offset1:1
	v_add_f32_e32 v240, v240, v82
	v_add_f32_e32 v241, v241, v68
	s_waitcnt lgkmcnt(6)
	v_mfma_f32_32x32x16_bf16 v[50:65], v[192:195], v[94:97], v[50:65]
	ds_read2_b64 v[192:195], v246 offset0:12 offset1:14
	v_add_u32_e32 v214, 0x5900, v251
	ds_write2_b64 v214, v[134:135], v[136:137] offset1:1
	v_add_f32_e32 v238, v238, v177
	v_add_f32_e32 v239, v239, v169
	s_waitcnt lgkmcnt(6)
	v_mfma_f32_32x32x16_bf16 v[34:49], v[206:209], v[94:97], v[34:49]
	ds_read2_b64 v[206:209], v247 offset0:44 offset1:46
	v_add_u32_e32 v214, 0x6a00, v251
	ds_write2_b64 v214, v[138:139], v[140:141] offset1:1
	v_add_f32_e32 v240, v240, v83
	v_add_f32_e32 v241, v241, v69
	s_waitcnt lgkmcnt(6)
	v_mfma_f32_32x32x16_bf16 v[18:33], v[210:213], v[94:97], v[18:33]
	ds_read2_b64 v[210:213], v248 offset0:76 offset1:78
	v_add_u32_e32 v214, 0x7b00, v251
	ds_write2_b64 v214, v[142:143], v[144:145] offset1:1
	v_add_f32_e32 v238, v238, v174
	v_add_f32_e32 v239, v239, v88
	s_waitcnt lgkmcnt(7)
	v_mfma_f32_32x32x16_bf16 v[2:17], v[222:225], v[94:97], v[2:17]
	ds_read2_b64 v[222:225], v249 offset0:108 offset1:110
	global_load_dwordx4 v[114:117], v[156:157], off offset:-2048
	global_load_dwordx4 v[118:121], v[156:157], off offset:2048
	v_add_f32_e32 v240, v240, v74
	v_add_f32_e32 v241, v241, v66
	s_waitcnt lgkmcnt(6)
	v_mfma_f32_32x32x16_bf16 v[50:65], v[192:195], v[188:191], v[50:65]
	global_load_dwordx4 v[122:125], v[158:159], off offset:-2048
	global_load_dwordx4 v[126:129], v[158:159], off offset:2048
	v_add_f32_e32 v238, v238, v175
	v_add_f32_e32 v239, v239, v89
	s_waitcnt lgkmcnt(4)
	v_mfma_f32_32x32x16_bf16 v[34:49], v[206:209], v[188:191], v[34:49]
	global_load_dwordx4 v[130:133], v[160:161], off offset:384
	global_load_dwordx4 v[134:137], v[162:163], off offset:384
	v_add_f32_e32 v240, v240, v75
	v_add_f32_e32 v241, v241, v67
	s_waitcnt lgkmcnt(2)
	v_mfma_f32_32x32x16_bf16 v[18:33], v[210:213], v[188:191], v[18:33]
	global_load_dwordx4 v[138:141], v[164:165], off offset:384
	global_load_dwordx4 v[142:145], v[166:167], off offset:384
	v_add_f32_e32 v238, v238, v239
	v_add_f32_e32 v240, v240, v241
	s_waitcnt lgkmcnt(0)
	v_mfma_f32_32x32x16_bf16 v[2:17], v[222:225], v[188:191], v[2:17]
	v_add_f32_e32 v238, v238, v240
	s_setprio 0
	s_branch .LBB0_266
